# v46: v45 + the same up-front A-fragment LDS reads in RG-LRU pass 2's tile loop
# speedup vs baseline: 1.0084x; 1.0019x over previous
.LBB0_602:
	v_add_u32_e32 v97, 0, v172
	v_add_u32_e32 v92, 0x10c00, v97
	v_add_u32_e32 v98, 0x10c40, v97
	ds_read_b128 v[92:95], v92
	ds_read_b128 v[102:105], v98
	v_add_u32_e32 v228, 0x10c80, v97
	ds_read_b128 v[228:231], v228
	v_add_u32_e32 v232, 0x10cc0, v97
	ds_read_b128 v[232:235], v232
	v_add_u32_e32 v173, 0, v171
	v_add_u32_e32 v180, 0x8c00, v173
	s_waitcnt lgkmcnt(3)
	v_mfma_f32_16x16x32_bf16 v[98:101], v[92:95], v[0:3], 0
	s_add_i32 s14, s14, -1
	v_add_u32_e32 v172, 0x1100, v172
	v_add_u32_e32 v171, 0x2100, v171
	v_mfma_f32_16x16x32_bf16 v[110:113], v[92:95], v[32:35], 0
	v_add_u32_e32 v195, 0x400, v173
	s_cmp_eq_u32 s14, 0
	v_mfma_f32_16x16x32_bf16 v[106:109], v[92:95], v[16:19], 0
	v_mfma_f32_16x16x32_bf16 v[92:95], v[92:95], v[48:51], 0
	s_waitcnt lgkmcnt(2)
	v_mfma_f32_16x16x32_bf16 v[114:117], v[102:105], v[4:7], v[98:101]
	v_mfma_f32_16x16x32_bf16 v[98:101], v[102:105], v[36:39], v[110:113]
	v_mfma_f32_16x16x32_bf16 v[174:177], v[102:105], v[20:23], v[106:109]
	v_mfma_f32_16x16x32_bf16 v[106:109], v[102:105], v[52:55], v[92:95]
	v_add_u32_e32 v97, 0x8800, v173
	s_waitcnt lgkmcnt(1)
	v_mfma_f32_16x16x32_bf16 v[102:105], v[228:231], v[8:11], v[114:117]
	v_mfma_f32_16x16x32_bf16 v[114:117], v[228:231], v[24:27], v[174:177]
	s_nop 2
	ds_read2_b32 v[174:175], v97 offset1:16
	ds_read2_b32 v[176:177], v97 offset0:132 offset1:148
	ds_read2_b32 v[178:179], v180 offset0:8 offset1:24
	ds_read2_b32 v[180:181], v180 offset0:140 offset1:156
	s_waitcnt lgkmcnt(3)
	v_mov_b32_e32 v183, v174
	v_mfma_f32_16x16x32_bf16 v[98:101], v[228:231], v[40:43], v[98:101]
	s_waitcnt lgkmcnt(0)
	v_mov_b32_e32 v184, v181
	v_mfma_f32_16x16x32_bf16 v[106:109], v[228:231], v[56:59], v[106:109]
	v_mfma_f32_16x16x32_bf16 v[102:105], v[232:235], v[12:15], v[102:105]
	v_mfma_f32_16x16x32_bf16 v[110:113], v[232:235], v[28:31], v[114:117]
	v_mfma_f32_16x16x32_bf16 v[98:101], v[232:235], v[44:47], v[98:101]
	s_nop 5
	v_fmamk_f32 v97, v102, 0xbfb8aa3b, v163
	v_fmamk_f32 v102, v103, 0xbfb8aa3b, v163
	v_fmamk_f32 v103, v104, 0xbfb8aa3b, v163
	v_mfma_f32_16x16x32_bf16 v[92:95], v[232:235], v[60:63], v[106:109]
	v_fmamk_f32 v104, v105, 0xbfb8aa3b, v163
	v_fmamk_f32 v98, v98, 0xbfb8aa3b, v164
	v_fmamk_f32 v99, v99, 0xbfb8aa3b, v164
	v_fmamk_f32 v100, v100, 0xbfb8aa3b, v164
	v_fmamk_f32 v101, v101, 0xbfb8aa3b, v164
	v_fmamk_f32 v105, v110, 0xbfb8aa3b, v168
	s_nop 1
	v_fmamk_f32 v92, v92, 0xbfb8aa3b, v167
	v_fmamk_f32 v106, v111, 0xbfb8aa3b, v168
	s_nop 0
	v_fmamk_f32 v93, v93, 0xbfb8aa3b, v167
	v_fmamk_f32 v107, v112, 0xbfb8aa3b, v168
	v_fmamk_f32 v94, v94, 0xbfb8aa3b, v167
	v_fmamk_f32 v108, v113, 0xbfb8aa3b, v168
	v_exp_f32_e32 v97, v97
	v_exp_f32_e32 v98, v98
	v_exp_f32_e32 v102, v102
	v_exp_f32_e32 v99, v99
	v_exp_f32_e32 v103, v103
	v_exp_f32_e32 v100, v100
	v_exp_f32_e32 v104, v104
	v_exp_f32_e32 v101, v101
	v_exp_f32_e32 v105, v105
	v_exp_f32_e32 v92, v92
	v_exp_f32_e32 v106, v106
	v_fmamk_f32 v95, v95, 0xbfb8aa3b, v167
	v_exp_f32_e32 v93, v93
	v_exp_f32_e32 v107, v107
	v_exp_f32_e32 v94, v94
	v_exp_f32_e32 v108, v108
	v_exp_f32_e32 v95, v95
	v_add_f32_e32 v97, 1.0, v97
	v_add_f32_e32 v98, 1.0, v98
	v_add_f32_e32 v102, 1.0, v102
	v_add_f32_e32 v99, 1.0, v99
	v_add_f32_e32 v103, 1.0, v103
	v_add_f32_e32 v100, 1.0, v100
	v_add_f32_e32 v104, 1.0, v104
	v_add_f32_e32 v101, 1.0, v101
	v_add_f32_e32 v105, 1.0, v105
	v_add_f32_e32 v92, 1.0, v92
	v_add_f32_e32 v106, 1.0, v106
	v_rcp_f32_e32 v97, v97
	v_add_f32_e32 v93, 1.0, v93
	v_add_f32_e32 v107, 1.0, v107
	v_add_f32_e32 v94, 1.0, v94
	v_add_f32_e32 v108, 1.0, v108
	v_rcp_f32_e32 v109, v98
	v_rcp_f32_e32 v98, v102
	v_rcp_f32_e32 v110, v99
	v_rcp_f32_e32 v99, v103
	v_rcp_f32_e32 v111, v100
	v_rcp_f32_e32 v100, v104
	v_rcp_f32_e32 v112, v101
	v_rcp_f32_e32 v101, v105
	v_rcp_f32_e32 v105, v92
	v_rcp_f32_e32 v92, v106
	v_rcp_f32_e32 v113, v93
	v_rcp_f32_e32 v93, v107
	v_rcp_f32_e32 v107, v94
	v_rcp_f32_e32 v94, v108
	v_add_f32_e32 v95, 1.0, v95
	v_rcp_f32_e32 v174, v95
	v_mul_f32_e32 v95, v97, v165
	v_mul_f32_e32 v97, v98, v165
	v_mul_f32_e32 v98, v99, v165
	v_mul_f32_e32 v99, v100, v165
	v_mul_f32_e32 v100, v101, v166
	v_mul_f32_e32 v92, v92, v166
	v_mul_f32_e32 v93, v93, v166
	v_mul_f32_e32 v94, v94, v166
	v_mov_b32_e32 v101, v92
	v_exp_f32_e32 v182, v95
	v_mov_b32_e32 v114, v177
	v_exp_f32_e32 v177, v97
	v_exp_f32_e32 v92, v100
	v_exp_f32_e32 v115, v101
	v_exp_f32_e32 v181, v99
	v_exp_f32_e32 v117, v93
	v_exp_f32_e32 v185, v94
	v_mov_b32_e32 v116, v179
	v_exp_f32_e32 v179, v98
	v_fma_f32 v93, -v182, v182, 1.0
	v_fma_f32 v94, -v177, v177, 1.0
	v_fma_f32 v99, -v92, v92, 1.0
	v_fma_f32 v100, -v115, v115, 1.0
	v_max_f32_e32 v93, 0, v93
	v_fma_f32 v97, -v181, v181, 1.0
	v_fma_f32 v101, -v117, v117, 1.0
	v_fma_f32 v102, -v185, v185, 1.0
	v_max_f32_e32 v94, 0, v94
	v_max_f32_e32 v99, 0, v99
	v_max_f32_e32 v100, 0, v100
	v_sqrt_f32_e32 v93, v93
	v_fma_f32 v95, -v179, v179, 1.0
	v_mul_f32_e32 v98, v182, v177
	v_mul_f32_e32 v103, v92, v115
	v_max_f32_e32 v97, 0, v97
	v_max_f32_e32 v101, 0, v101
	v_max_f32_e32 v102, 0, v102
	v_sqrt_f32_e32 v104, v94
	v_sqrt_f32_e32 v186, v99
	v_sqrt_f32_e32 v187, v100
	v_max_f32_e32 v95, 0, v95
	v_mul_f32_e32 v98, v179, v98
	v_mul_f32_e32 v103, v117, v103
	v_sqrt_f32_e32 v108, v97
	v_sqrt_f32_e32 v188, v101
	v_sqrt_f32_e32 v189, v102
	v_sqrt_f32_e32 v106, v95
	v_mul_f32_e32 v95, v181, v98
	v_mul_f32_e32 v97, v185, v103
	ds_bpermute_b32 v94, v129, v95
	ds_bpermute_b32 v98, v170, v95
	ds_bpermute_b32 v100, v131, v95
	ds_bpermute_b32 v102, v169, v95
	ds_bpermute_b32 v95, v129, v97
	ds_bpermute_b32 v99, v170, v97
	ds_bpermute_b32 v101, v131, v97
	ds_bpermute_b32 v103, v169, v97
	v_mul_f32_e32 v97, v109, v93
	v_mul_f32_e32 v104, v110, v104
	v_mul_f32_e32 v93, v105, v186
	v_mul_f32_e32 v110, v113, v187
	v_pk_mul_f32 v[186:187], v[182:183], v[96:97]
	v_mul_f32_e32 v108, v112, v108
	v_mul_f32_e32 v112, v107, v188
	v_mul_f32_e32 v174, v174, v189
	v_pk_fma_f32 v[188:189], v[182:183], v[96:97], v[186:187] op_sel_hi:[1,1,0]
	v_mov_b32_e32 v97, v175
	v_mov_b32_e32 v105, v189
	v_pk_mul_f32 v[188:189], v[92:93], v[96:97]
	v_pk_mul_f32 v[190:191], v[176:177], v[104:105]
	v_pk_fma_f32 v[192:193], v[92:93], v[96:97], v[188:189] op_sel_hi:[1,1,0]
	v_mul_f32_e32 v106, v111, v106
	v_pk_fma_f32 v[104:105], v[176:177], v[104:105], v[190:191] op_sel_hi:[1,1,0]
	v_mov_b32_e32 v111, v193
	v_mov_b32_e32 v107, v105
	v_pk_mul_f32 v[104:105], v[110:111], v[114:115]
	v_pk_mul_f32 v[192:193], v[178:179], v[106:107]
	v_pk_fma_f32 v[110:111], v[110:111], v[114:115], v[104:105] op_sel_hi:[1,1,0]
	v_pk_fma_f32 v[106:107], v[178:179], v[106:107], v[192:193] op_sel_hi:[1,1,0]
	v_mov_b32_e32 v113, v111
	v_mov_b32_e32 v109, v107
	v_pk_mul_f32 v[106:107], v[112:113], v[116:117]
	v_pk_mul_f32 v[110:111], v[180:181], v[108:109]
	v_pk_fma_f32 v[112:113], v[112:113], v[116:117], v[106:107] op_sel_hi:[1,1,0]
	v_pk_fma_f32 v[108:109], v[180:181], v[108:109], v[110:111] op_sel:[0,0,1] op_sel_hi:[1,1,0]
	v_mov_b32_e32 v175, v113
	v_pk_mul_f32 v[202:203], v[174:175], v[184:185]
	ds_bpermute_b32 v112, v129, v108
	v_pk_fma_f32 v[174:175], v[174:175], v[184:185], v[202:203] op_sel:[0,0,1] op_sel_hi:[1,1,0]
	ds_bpermute_b32 v113, v129, v174
	ds_bpermute_b32 v198, v170, v108
	ds_bpermute_b32 v199, v170, v174
	ds_bpermute_b32 v200, v131, v108
	ds_bpermute_b32 v201, v131, v174
	ds_bpermute_b32 v108, v169, v108
	ds_bpermute_b32 v109, v169, v174
	s_waitcnt lgkmcnt(6)
	v_pk_fma_f32 v[94:95], v[142:143], v[94:95], v[112:113]
	s_nop 0
	v_cndmask_b32_e64 v93, v142, v94, s[58:59]
	s_waitcnt lgkmcnt(4)
	v_pk_fma_f32 v[98:99], v[94:95], v[98:99], v[198:199]
	v_cndmask_b32_e64 v97, v143, v95, s[58:59]
	v_cndmask_b32_e64 v93, v93, v98, s[60:61]
	s_waitcnt lgkmcnt(2)
	v_pk_fma_f32 v[94:95], v[98:99], v[100:101], v[200:201]
	v_cndmask_b32_e64 v97, v97, v99, s[60:61]
	v_cndmask_b32_e64 v93, v93, v94, s[62:63]
	s_waitcnt lgkmcnt(0)
	v_pk_fma_f32 v[142:143], v[94:95], v[102:103], v[108:109]
	v_cndmask_b32_e64 v94, v97, v95, s[62:63]
	v_cndmask_b32_e64 v93, v93, v142, s[56:57]
	v_cndmask_b32_e64 v94, v94, v143, s[56:57]
	v_fmac_f32_e32 v187, v182, v93
	v_fmac_f32_e32 v189, v92, v94
	v_fmac_f32_e32 v190, v177, v187
	v_fmac_f32_e32 v104, v115, v189
	v_fmac_f32_e32 v192, v179, v190
	v_fmac_f32_e32 v106, v117, v104
	v_fmac_f32_e32 v110, v181, v192
	v_fmac_f32_e32 v202, v185, v106
	ds_write2_b32 v173, v187, v189 offset1:16
	ds_write2_b32 v173, v190, v104 offset0:132 offset1:148
	ds_write2_b32 v195, v192, v106 offset0:8 offset1:24
	ds_write2_b32 v195, v110, v202 offset0:140 offset1:156
	s_cbranch_scc0 .LBB0_602
	s_branch .LBB0_581
